# chunk-state scan rewritten by hand: 64 steps unrolled, loads two groups ahead (same arithmetic)
# baseline (speedup 1.0000x reference)
.LBB0_351:
	s_waitcnt lgkmcnt(0)
	v_lshl_add_u64 v[10:11], s[34:35], 0, v[8:9]
	v_lshl_add_u64 v[14:15], s[34:35], 0, v[6:7]
	s_mov_b32 s4, 0x80000
	s_mov_b32 s5, 0
	s_movk_i32 s6, 0x800
	s_mov_b32 s7, 0
	s_mov_b32 s8, 0xb000000
	s_mov_b32 s9, 0
	s_mov_b32 s10, 0x2000000
	s_mov_b32 s11, 0
	s_mov_b32 s12, 0xf00000
	s_mov_b32 s13, 0
	v_lshl_add_u64 v[16:17], s[8:9], 0, v[10:11]
	v_lshl_add_u64 v[18:19], s[10:11], 0, v[10:11]
	v_lshl_add_u64 v[20:21], s[12:13], 0, v[14:15]
	global_load_dword v24, v[16:17], off
	global_load_dwordx2 v[48:49], v[20:21], off
	v_lshl_add_u64 v[16:17], s[4:5], 0, v[16:17]
	v_lshl_add_u64 v[20:21], s[6:7], 0, v[20:21]
	global_load_dword v25, v[16:17], off
	global_load_dwordx2 v[50:51], v[20:21], off
	v_lshl_add_u64 v[16:17], s[4:5], 0, v[16:17]
	v_lshl_add_u64 v[20:21], s[6:7], 0, v[20:21]
	global_load_dword v26, v[16:17], off
	global_load_dwordx2 v[52:53], v[20:21], off
	v_lshl_add_u64 v[16:17], s[4:5], 0, v[16:17]
	v_lshl_add_u64 v[20:21], s[6:7], 0, v[20:21]
	global_load_dword v27, v[16:17], off
	global_load_dwordx2 v[54:55], v[20:21], off
	v_lshl_add_u64 v[16:17], s[4:5], 0, v[16:17]
	v_lshl_add_u64 v[20:21], s[6:7], 0, v[20:21]
	global_load_dword v28, v[16:17], off
	global_load_dwordx2 v[56:57], v[20:21], off
	v_lshl_add_u64 v[16:17], s[4:5], 0, v[16:17]
	v_lshl_add_u64 v[20:21], s[6:7], 0, v[20:21]
	global_load_dword v29, v[16:17], off
	global_load_dwordx2 v[58:59], v[20:21], off
	v_lshl_add_u64 v[16:17], s[4:5], 0, v[16:17]
	v_lshl_add_u64 v[20:21], s[6:7], 0, v[20:21]
	global_load_dword v30, v[16:17], off
	global_load_dwordx2 v[60:61], v[20:21], off
	v_lshl_add_u64 v[16:17], s[4:5], 0, v[16:17]
	v_lshl_add_u64 v[20:21], s[6:7], 0, v[20:21]
	global_load_dword v31, v[16:17], off
	global_load_dwordx2 v[62:63], v[20:21], off
	v_lshl_add_u64 v[16:17], s[4:5], 0, v[16:17]
	v_lshl_add_u64 v[20:21], s[6:7], 0, v[20:21]
	global_load_dword v32, v[16:17], off
	global_load_dwordx2 v[64:65], v[20:21], off
	v_lshl_add_u64 v[16:17], s[4:5], 0, v[16:17]
	v_lshl_add_u64 v[20:21], s[6:7], 0, v[20:21]
	global_load_dword v33, v[16:17], off
	global_load_dwordx2 v[66:67], v[20:21], off
	v_lshl_add_u64 v[16:17], s[4:5], 0, v[16:17]
	v_lshl_add_u64 v[20:21], s[6:7], 0, v[20:21]
	global_load_dword v34, v[16:17], off
	global_load_dwordx2 v[68:69], v[20:21], off
	v_lshl_add_u64 v[16:17], s[4:5], 0, v[16:17]
	v_lshl_add_u64 v[20:21], s[6:7], 0, v[20:21]
	global_load_dword v35, v[16:17], off
	global_load_dwordx2 v[70:71], v[20:21], off
	v_lshl_add_u64 v[16:17], s[4:5], 0, v[16:17]
	v_lshl_add_u64 v[20:21], s[6:7], 0, v[20:21]
	global_load_dword v36, v[16:17], off
	global_load_dwordx2 v[72:73], v[20:21], off
	v_lshl_add_u64 v[16:17], s[4:5], 0, v[16:17]
	v_lshl_add_u64 v[20:21], s[6:7], 0, v[20:21]
	global_load_dword v37, v[16:17], off
	global_load_dwordx2 v[74:75], v[20:21], off
	v_lshl_add_u64 v[16:17], s[4:5], 0, v[16:17]
	v_lshl_add_u64 v[20:21], s[6:7], 0, v[20:21]
	global_load_dword v38, v[16:17], off
	global_load_dwordx2 v[76:77], v[20:21], off
	v_lshl_add_u64 v[16:17], s[4:5], 0, v[16:17]
	v_lshl_add_u64 v[20:21], s[6:7], 0, v[20:21]
	global_load_dword v39, v[16:17], off
	global_load_dwordx2 v[78:79], v[20:21], off
	v_lshl_add_u64 v[16:17], s[4:5], 0, v[16:17]
	v_lshl_add_u64 v[20:21], s[6:7], 0, v[20:21]
	v_mov_b32_e32 v12, 0
	v_mov_b32_e32 v13, 0
	v_cvt_pk_bf16_f32 v98, v12, v13
	global_store_dword v[18:19], v98, off
	v_lshl_add_u64 v[18:19], s[4:5], 0, v[18:19]
	s_waitcnt vmcnt(32)
	v_lshlrev_b32_e32 v22, 16, v24
	v_and_b32_e32 v23, 0xffff0000, v24
	v_add_f32_e32 v12, v12, v22
	v_add_f32_e32 v13, v13, v23
	s_waitcnt vmcnt(31)
	v_mul_f32_e32 v96, v48, v12
	v_mul_f32_e32 v97, v49, v13
	s_waitcnt vmcnt(30)
	v_lshlrev_b32_e32 v22, 16, v25
	v_and_b32_e32 v23, 0xffff0000, v25
	v_fma_f32 v12, v48, v12, v22
	v_fma_f32 v13, v49, v13, v23
	v_cvt_pk_bf16_f32 v98, v96, v97
	global_store_dword v[18:19], v98, off
	v_lshl_add_u64 v[18:19], s[4:5], 0, v[18:19]
	s_waitcnt vmcnt(30)
	v_mul_f32_e32 v96, v50, v12
	v_mul_f32_e32 v97, v51, v13
	s_waitcnt vmcnt(29)
	v_lshlrev_b32_e32 v22, 16, v26
	v_and_b32_e32 v23, 0xffff0000, v26
	v_fma_f32 v12, v50, v12, v22
	v_fma_f32 v13, v51, v13, v23
	v_cvt_pk_bf16_f32 v98, v96, v97
	global_store_dword v[18:19], v98, off
	v_lshl_add_u64 v[18:19], s[4:5], 0, v[18:19]
	s_waitcnt vmcnt(29)
	v_mul_f32_e32 v96, v52, v12
	v_mul_f32_e32 v97, v53, v13
	s_waitcnt vmcnt(28)
	v_lshlrev_b32_e32 v22, 16, v27
	v_and_b32_e32 v23, 0xffff0000, v27
	v_fma_f32 v12, v52, v12, v22
	v_fma_f32 v13, v53, v13, v23
	v_cvt_pk_bf16_f32 v98, v96, v97
	global_store_dword v[18:19], v98, off
	v_lshl_add_u64 v[18:19], s[4:5], 0, v[18:19]
	s_waitcnt vmcnt(28)
	v_mul_f32_e32 v96, v54, v12
	v_mul_f32_e32 v97, v55, v13
	s_waitcnt vmcnt(27)
	v_lshlrev_b32_e32 v22, 16, v28
	v_and_b32_e32 v23, 0xffff0000, v28
	v_fma_f32 v12, v54, v12, v22
	v_fma_f32 v13, v55, v13, v23
	v_cvt_pk_bf16_f32 v98, v96, v97
	global_store_dword v[18:19], v98, off
	v_lshl_add_u64 v[18:19], s[4:5], 0, v[18:19]
	global_load_dword v40, v[16:17], off
	global_load_dwordx2 v[80:81], v[20:21], off
	v_lshl_add_u64 v[16:17], s[4:5], 0, v[16:17]
	v_lshl_add_u64 v[20:21], s[6:7], 0, v[20:21]
	global_load_dword v41, v[16:17], off
	global_load_dwordx2 v[82:83], v[20:21], off
	v_lshl_add_u64 v[16:17], s[4:5], 0, v[16:17]
	v_lshl_add_u64 v[20:21], s[6:7], 0, v[20:21]
	global_load_dword v42, v[16:17], off
	global_load_dwordx2 v[84:85], v[20:21], off
	v_lshl_add_u64 v[16:17], s[4:5], 0, v[16:17]
	v_lshl_add_u64 v[20:21], s[6:7], 0, v[20:21]
	global_load_dword v43, v[16:17], off
	global_load_dwordx2 v[86:87], v[20:21], off
	v_lshl_add_u64 v[16:17], s[4:5], 0, v[16:17]
	v_lshl_add_u64 v[20:21], s[6:7], 0, v[20:21]
	global_load_dword v44, v[16:17], off
	global_load_dwordx2 v[88:89], v[20:21], off
	v_lshl_add_u64 v[16:17], s[4:5], 0, v[16:17]
	v_lshl_add_u64 v[20:21], s[6:7], 0, v[20:21]
	global_load_dword v45, v[16:17], off
	global_load_dwordx2 v[90:91], v[20:21], off
	v_lshl_add_u64 v[16:17], s[4:5], 0, v[16:17]
	v_lshl_add_u64 v[20:21], s[6:7], 0, v[20:21]
	global_load_dword v46, v[16:17], off
	global_load_dwordx2 v[92:93], v[20:21], off
	v_lshl_add_u64 v[16:17], s[4:5], 0, v[16:17]
	v_lshl_add_u64 v[20:21], s[6:7], 0, v[20:21]
	global_load_dword v47, v[16:17], off
	global_load_dwordx2 v[94:95], v[20:21], off
	v_lshl_add_u64 v[16:17], s[4:5], 0, v[16:17]
	v_lshl_add_u64 v[20:21], s[6:7], 0, v[20:21]
	s_waitcnt vmcnt(43)
	v_mul_f32_e32 v96, v56, v12
	v_mul_f32_e32 v97, v57, v13
	s_waitcnt vmcnt(42)
	v_lshlrev_b32_e32 v22, 16, v29
	v_and_b32_e32 v23, 0xffff0000, v29
	v_fma_f32 v12, v56, v12, v22
	v_fma_f32 v13, v57, v13, v23
	v_cvt_pk_bf16_f32 v98, v96, v97
	global_store_dword v[18:19], v98, off
	v_lshl_add_u64 v[18:19], s[4:5], 0, v[18:19]
	s_waitcnt vmcnt(42)
	v_mul_f32_e32 v96, v58, v12
	v_mul_f32_e32 v97, v59, v13
	s_waitcnt vmcnt(41)
	v_lshlrev_b32_e32 v22, 16, v30
	v_and_b32_e32 v23, 0xffff0000, v30
	v_fma_f32 v12, v58, v12, v22
	v_fma_f32 v13, v59, v13, v23
	v_cvt_pk_bf16_f32 v98, v96, v97
	global_store_dword v[18:19], v98, off
	v_lshl_add_u64 v[18:19], s[4:5], 0, v[18:19]
	s_waitcnt vmcnt(41)
	v_mul_f32_e32 v96, v60, v12
	v_mul_f32_e32 v97, v61, v13
	s_waitcnt vmcnt(40)
	v_lshlrev_b32_e32 v22, 16, v31
	v_and_b32_e32 v23, 0xffff0000, v31
	v_fma_f32 v12, v60, v12, v22
	v_fma_f32 v13, v61, v13, v23
	v_cvt_pk_bf16_f32 v98, v96, v97
	global_store_dword v[18:19], v98, off
	v_lshl_add_u64 v[18:19], s[4:5], 0, v[18:19]
	s_waitcnt vmcnt(40)
	v_mul_f32_e32 v12, v62, v12
	v_mul_f32_e32 v13, v63, v13
	v_cvt_pk_bf16_f32 v98, v12, v13
	global_store_dword v[18:19], v98, off
	v_lshl_add_u64 v[18:19], s[4:5], 0, v[18:19]
	s_waitcnt vmcnt(40)
	v_lshlrev_b32_e32 v22, 16, v32
	v_and_b32_e32 v23, 0xffff0000, v32
	v_add_f32_e32 v12, v12, v22
	v_add_f32_e32 v13, v13, v23
	s_waitcnt vmcnt(39)
	v_mul_f32_e32 v96, v64, v12
	v_mul_f32_e32 v97, v65, v13
	s_waitcnt vmcnt(38)
	v_lshlrev_b32_e32 v22, 16, v33
	v_and_b32_e32 v23, 0xffff0000, v33
	v_fma_f32 v12, v64, v12, v22
	v_fma_f32 v13, v65, v13, v23
	v_cvt_pk_bf16_f32 v98, v96, v97
	global_store_dword v[18:19], v98, off
	v_lshl_add_u64 v[18:19], s[4:5], 0, v[18:19]
	s_waitcnt vmcnt(38)
	v_mul_f32_e32 v96, v66, v12
	v_mul_f32_e32 v97, v67, v13
	s_waitcnt vmcnt(37)
	v_lshlrev_b32_e32 v22, 16, v34
	v_and_b32_e32 v23, 0xffff0000, v34
	v_fma_f32 v12, v66, v12, v22
	v_fma_f32 v13, v67, v13, v23
	v_cvt_pk_bf16_f32 v98, v96, v97
	global_store_dword v[18:19], v98, off
	v_lshl_add_u64 v[18:19], s[4:5], 0, v[18:19]
	s_waitcnt vmcnt(37)
	v_mul_f32_e32 v96, v68, v12
	v_mul_f32_e32 v97, v69, v13
	s_waitcnt vmcnt(36)
	v_lshlrev_b32_e32 v22, 16, v35
	v_and_b32_e32 v23, 0xffff0000, v35
	v_fma_f32 v12, v68, v12, v22
	v_fma_f32 v13, v69, v13, v23
	v_cvt_pk_bf16_f32 v98, v96, v97
	global_store_dword v[18:19], v98, off
	v_lshl_add_u64 v[18:19], s[4:5], 0, v[18:19]
	s_waitcnt vmcnt(36)
	v_mul_f32_e32 v96, v70, v12
	v_mul_f32_e32 v97, v71, v13
	s_waitcnt vmcnt(35)
	v_lshlrev_b32_e32 v22, 16, v36
	v_and_b32_e32 v23, 0xffff0000, v36
	v_fma_f32 v12, v70, v12, v22
	v_fma_f32 v13, v71, v13, v23
	v_cvt_pk_bf16_f32 v98, v96, v97
	global_store_dword v[18:19], v98, off
	v_lshl_add_u64 v[18:19], s[4:5], 0, v[18:19]
	global_load_dword v24, v[16:17], off
	global_load_dwordx2 v[48:49], v[20:21], off
	v_lshl_add_u64 v[16:17], s[4:5], 0, v[16:17]
	v_lshl_add_u64 v[20:21], s[6:7], 0, v[20:21]
	global_load_dword v25, v[16:17], off
	global_load_dwordx2 v[50:51], v[20:21], off
	v_lshl_add_u64 v[16:17], s[4:5], 0, v[16:17]
	v_lshl_add_u64 v[20:21], s[6:7], 0, v[20:21]
	global_load_dword v26, v[16:17], off
	global_load_dwordx2 v[52:53], v[20:21], off
	v_lshl_add_u64 v[16:17], s[4:5], 0, v[16:17]
	v_lshl_add_u64 v[20:21], s[6:7], 0, v[20:21]
	global_load_dword v27, v[16:17], off
	global_load_dwordx2 v[54:55], v[20:21], off
	v_lshl_add_u64 v[16:17], s[4:5], 0, v[16:17]
	v_lshl_add_u64 v[20:21], s[6:7], 0, v[20:21]
	global_load_dword v28, v[16:17], off
	global_load_dwordx2 v[56:57], v[20:21], off
	v_lshl_add_u64 v[16:17], s[4:5], 0, v[16:17]
	v_lshl_add_u64 v[20:21], s[6:7], 0, v[20:21]
	global_load_dword v29, v[16:17], off
	global_load_dwordx2 v[58:59], v[20:21], off
	v_lshl_add_u64 v[16:17], s[4:5], 0, v[16:17]
	v_lshl_add_u64 v[20:21], s[6:7], 0, v[20:21]
	global_load_dword v30, v[16:17], off
	global_load_dwordx2 v[60:61], v[20:21], off
	v_lshl_add_u64 v[16:17], s[4:5], 0, v[16:17]
	v_lshl_add_u64 v[20:21], s[6:7], 0, v[20:21]
	global_load_dword v31, v[16:17], off
	global_load_dwordx2 v[62:63], v[20:21], off
	v_lshl_add_u64 v[16:17], s[4:5], 0, v[16:17]
	v_lshl_add_u64 v[20:21], s[6:7], 0, v[20:21]
	s_waitcnt vmcnt(51)
	v_mul_f32_e32 v96, v72, v12
	v_mul_f32_e32 v97, v73, v13
	s_waitcnt vmcnt(50)
	v_lshlrev_b32_e32 v22, 16, v37
	v_and_b32_e32 v23, 0xffff0000, v37
	v_fma_f32 v12, v72, v12, v22
	v_fma_f32 v13, v73, v13, v23
	v_cvt_pk_bf16_f32 v98, v96, v97
	global_store_dword v[18:19], v98, off
	v_lshl_add_u64 v[18:19], s[4:5], 0, v[18:19]
	s_waitcnt vmcnt(50)
	v_mul_f32_e32 v96, v74, v12
	v_mul_f32_e32 v97, v75, v13
	s_waitcnt vmcnt(49)
	v_lshlrev_b32_e32 v22, 16, v38
	v_and_b32_e32 v23, 0xffff0000, v38
	v_fma_f32 v12, v74, v12, v22
	v_fma_f32 v13, v75, v13, v23
	v_cvt_pk_bf16_f32 v98, v96, v97
	global_store_dword v[18:19], v98, off
	v_lshl_add_u64 v[18:19], s[4:5], 0, v[18:19]
	s_waitcnt vmcnt(49)
	v_mul_f32_e32 v96, v76, v12
	v_mul_f32_e32 v97, v77, v13
	s_waitcnt vmcnt(48)
	v_lshlrev_b32_e32 v22, 16, v39
	v_and_b32_e32 v23, 0xffff0000, v39
	v_fma_f32 v12, v76, v12, v22
	v_fma_f32 v13, v77, v13, v23
	v_cvt_pk_bf16_f32 v98, v96, v97
	global_store_dword v[18:19], v98, off
	v_lshl_add_u64 v[18:19], s[4:5], 0, v[18:19]
	s_waitcnt vmcnt(48)
	v_mul_f32_e32 v12, v78, v12
	v_mul_f32_e32 v13, v79, v13
	v_cvt_pk_bf16_f32 v98, v12, v13
	global_store_dword v[18:19], v98, off
	v_lshl_add_u64 v[18:19], s[4:5], 0, v[18:19]
	s_waitcnt vmcnt(43)
	v_lshlrev_b32_e32 v22, 16, v40
	v_and_b32_e32 v23, 0xffff0000, v40
	v_add_f32_e32 v12, v12, v22
	v_add_f32_e32 v13, v13, v23
	s_waitcnt vmcnt(42)
	v_mul_f32_e32 v96, v80, v12
	v_mul_f32_e32 v97, v81, v13
	s_waitcnt vmcnt(41)
	v_lshlrev_b32_e32 v22, 16, v41
	v_and_b32_e32 v23, 0xffff0000, v41
	v_fma_f32 v12, v80, v12, v22
	v_fma_f32 v13, v81, v13, v23
	v_cvt_pk_bf16_f32 v98, v96, v97
	global_store_dword v[18:19], v98, off
	v_lshl_add_u64 v[18:19], s[4:5], 0, v[18:19]
	s_waitcnt vmcnt(41)
	v_mul_f32_e32 v96, v82, v12
	v_mul_f32_e32 v97, v83, v13
	s_waitcnt vmcnt(40)
	v_lshlrev_b32_e32 v22, 16, v42
	v_and_b32_e32 v23, 0xffff0000, v42
	v_fma_f32 v12, v82, v12, v22
	v_fma_f32 v13, v83, v13, v23
	v_cvt_pk_bf16_f32 v98, v96, v97
	global_store_dword v[18:19], v98, off
	v_lshl_add_u64 v[18:19], s[4:5], 0, v[18:19]
	s_waitcnt vmcnt(40)
	v_mul_f32_e32 v96, v84, v12
	v_mul_f32_e32 v97, v85, v13
	s_waitcnt vmcnt(39)
	v_lshlrev_b32_e32 v22, 16, v43
	v_and_b32_e32 v23, 0xffff0000, v43
	v_fma_f32 v12, v84, v12, v22
	v_fma_f32 v13, v85, v13, v23
	v_cvt_pk_bf16_f32 v98, v96, v97
	global_store_dword v[18:19], v98, off
	v_lshl_add_u64 v[18:19], s[4:5], 0, v[18:19]
	s_waitcnt vmcnt(39)
	v_mul_f32_e32 v96, v86, v12
	v_mul_f32_e32 v97, v87, v13
	s_waitcnt vmcnt(38)
	v_lshlrev_b32_e32 v22, 16, v44
	v_and_b32_e32 v23, 0xffff0000, v44
	v_fma_f32 v12, v86, v12, v22
	v_fma_f32 v13, v87, v13, v23
	v_cvt_pk_bf16_f32 v98, v96, v97
	global_store_dword v[18:19], v98, off
	v_lshl_add_u64 v[18:19], s[4:5], 0, v[18:19]
	global_load_dword v32, v[16:17], off
	global_load_dwordx2 v[64:65], v[20:21], off
	v_lshl_add_u64 v[16:17], s[4:5], 0, v[16:17]
	v_lshl_add_u64 v[20:21], s[6:7], 0, v[20:21]
	global_load_dword v33, v[16:17], off
	global_load_dwordx2 v[66:67], v[20:21], off
	v_lshl_add_u64 v[16:17], s[4:5], 0, v[16:17]
	v_lshl_add_u64 v[20:21], s[6:7], 0, v[20:21]
	global_load_dword v34, v[16:17], off
	global_load_dwordx2 v[68:69], v[20:21], off
	v_lshl_add_u64 v[16:17], s[4:5], 0, v[16:17]
	v_lshl_add_u64 v[20:21], s[6:7], 0, v[20:21]
	global_load_dword v35, v[16:17], off
	global_load_dwordx2 v[70:71], v[20:21], off
	v_lshl_add_u64 v[16:17], s[4:5], 0, v[16:17]
	v_lshl_add_u64 v[20:21], s[6:7], 0, v[20:21]
	global_load_dword v36, v[16:17], off
	global_load_dwordx2 v[72:73], v[20:21], off
	v_lshl_add_u64 v[16:17], s[4:5], 0, v[16:17]
	v_lshl_add_u64 v[20:21], s[6:7], 0, v[20:21]
	global_load_dword v37, v[16:17], off
	global_load_dwordx2 v[74:75], v[20:21], off
	v_lshl_add_u64 v[16:17], s[4:5], 0, v[16:17]
	v_lshl_add_u64 v[20:21], s[6:7], 0, v[20:21]
	global_load_dword v38, v[16:17], off
	global_load_dwordx2 v[76:77], v[20:21], off
	v_lshl_add_u64 v[16:17], s[4:5], 0, v[16:17]
	v_lshl_add_u64 v[20:21], s[6:7], 0, v[20:21]
	global_load_dword v39, v[16:17], off
	global_load_dwordx2 v[78:79], v[20:21], off
	v_lshl_add_u64 v[16:17], s[4:5], 0, v[16:17]
	v_lshl_add_u64 v[20:21], s[6:7], 0, v[20:21]
	s_waitcnt vmcnt(54)
	v_mul_f32_e32 v96, v88, v12
	v_mul_f32_e32 v97, v89, v13
	s_waitcnt vmcnt(53)
	v_lshlrev_b32_e32 v22, 16, v45
	v_and_b32_e32 v23, 0xffff0000, v45
	v_fma_f32 v12, v88, v12, v22
	v_fma_f32 v13, v89, v13, v23
	v_cvt_pk_bf16_f32 v98, v96, v97
	global_store_dword v[18:19], v98, off
	v_lshl_add_u64 v[18:19], s[4:5], 0, v[18:19]
	s_waitcnt vmcnt(53)
	v_mul_f32_e32 v96, v90, v12
	v_mul_f32_e32 v97, v91, v13
	s_waitcnt vmcnt(52)
	v_lshlrev_b32_e32 v22, 16, v46
	v_and_b32_e32 v23, 0xffff0000, v46
	v_fma_f32 v12, v90, v12, v22
	v_fma_f32 v13, v91, v13, v23
	v_cvt_pk_bf16_f32 v98, v96, v97
	global_store_dword v[18:19], v98, off
	v_lshl_add_u64 v[18:19], s[4:5], 0, v[18:19]
	s_waitcnt vmcnt(52)
	v_mul_f32_e32 v96, v92, v12
	v_mul_f32_e32 v97, v93, v13
	s_waitcnt vmcnt(51)
	v_lshlrev_b32_e32 v22, 16, v47
	v_and_b32_e32 v23, 0xffff0000, v47
	v_fma_f32 v12, v92, v12, v22
	v_fma_f32 v13, v93, v13, v23
	v_cvt_pk_bf16_f32 v98, v96, v97
	global_store_dword v[18:19], v98, off
	v_lshl_add_u64 v[18:19], s[4:5], 0, v[18:19]
	s_waitcnt vmcnt(51)
	v_mul_f32_e32 v12, v94, v12
	v_mul_f32_e32 v13, v95, v13
	v_cvt_pk_bf16_f32 v98, v12, v13
	global_store_dword v[18:19], v98, off
	v_lshl_add_u64 v[18:19], s[4:5], 0, v[18:19]
	s_waitcnt vmcnt(43)
	v_lshlrev_b32_e32 v22, 16, v24
	v_and_b32_e32 v23, 0xffff0000, v24
	v_add_f32_e32 v12, v12, v22
	v_add_f32_e32 v13, v13, v23
	s_waitcnt vmcnt(42)
	v_mul_f32_e32 v96, v48, v12
	v_mul_f32_e32 v97, v49, v13
	s_waitcnt vmcnt(41)
	v_lshlrev_b32_e32 v22, 16, v25
	v_and_b32_e32 v23, 0xffff0000, v25
	v_fma_f32 v12, v48, v12, v22
	v_fma_f32 v13, v49, v13, v23
	v_cvt_pk_bf16_f32 v98, v96, v97
	global_store_dword v[18:19], v98, off
	v_lshl_add_u64 v[18:19], s[4:5], 0, v[18:19]
	s_waitcnt vmcnt(41)
	v_mul_f32_e32 v96, v50, v12
	v_mul_f32_e32 v97, v51, v13
	s_waitcnt vmcnt(40)
	v_lshlrev_b32_e32 v22, 16, v26
	v_and_b32_e32 v23, 0xffff0000, v26
	v_fma_f32 v12, v50, v12, v22
	v_fma_f32 v13, v51, v13, v23
	v_cvt_pk_bf16_f32 v98, v96, v97
	global_store_dword v[18:19], v98, off
	v_lshl_add_u64 v[18:19], s[4:5], 0, v[18:19]
	s_waitcnt vmcnt(40)
	v_mul_f32_e32 v96, v52, v12
	v_mul_f32_e32 v97, v53, v13
	s_waitcnt vmcnt(39)
	v_lshlrev_b32_e32 v22, 16, v27
	v_and_b32_e32 v23, 0xffff0000, v27
	v_fma_f32 v12, v52, v12, v22
	v_fma_f32 v13, v53, v13, v23
	v_cvt_pk_bf16_f32 v98, v96, v97
	global_store_dword v[18:19], v98, off
	v_lshl_add_u64 v[18:19], s[4:5], 0, v[18:19]
	s_waitcnt vmcnt(39)
	v_mul_f32_e32 v96, v54, v12
	v_mul_f32_e32 v97, v55, v13
	s_waitcnt vmcnt(38)
	v_lshlrev_b32_e32 v22, 16, v28
	v_and_b32_e32 v23, 0xffff0000, v28
	v_fma_f32 v12, v54, v12, v22
	v_fma_f32 v13, v55, v13, v23
	v_cvt_pk_bf16_f32 v98, v96, v97
	global_store_dword v[18:19], v98, off
	v_lshl_add_u64 v[18:19], s[4:5], 0, v[18:19]
	global_load_dword v40, v[16:17], off
	global_load_dwordx2 v[80:81], v[20:21], off
	v_lshl_add_u64 v[16:17], s[4:5], 0, v[16:17]
	v_lshl_add_u64 v[20:21], s[6:7], 0, v[20:21]
	global_load_dword v41, v[16:17], off
	global_load_dwordx2 v[82:83], v[20:21], off
	v_lshl_add_u64 v[16:17], s[4:5], 0, v[16:17]
	v_lshl_add_u64 v[20:21], s[6:7], 0, v[20:21]
	global_load_dword v42, v[16:17], off
	global_load_dwordx2 v[84:85], v[20:21], off
	v_lshl_add_u64 v[16:17], s[4:5], 0, v[16:17]
	v_lshl_add_u64 v[20:21], s[6:7], 0, v[20:21]
	global_load_dword v43, v[16:17], off
	global_load_dwordx2 v[86:87], v[20:21], off
	v_lshl_add_u64 v[16:17], s[4:5], 0, v[16:17]
	v_lshl_add_u64 v[20:21], s[6:7], 0, v[20:21]
	global_load_dword v44, v[16:17], off
	global_load_dwordx2 v[88:89], v[20:21], off
	v_lshl_add_u64 v[16:17], s[4:5], 0, v[16:17]
	v_lshl_add_u64 v[20:21], s[6:7], 0, v[20:21]
	global_load_dword v45, v[16:17], off
	global_load_dwordx2 v[90:91], v[20:21], off
	v_lshl_add_u64 v[16:17], s[4:5], 0, v[16:17]
	v_lshl_add_u64 v[20:21], s[6:7], 0, v[20:21]
	global_load_dword v46, v[16:17], off
	global_load_dwordx2 v[92:93], v[20:21], off
	v_lshl_add_u64 v[16:17], s[4:5], 0, v[16:17]
	v_lshl_add_u64 v[20:21], s[6:7], 0, v[20:21]
	global_load_dword v47, v[16:17], off
	global_load_dwordx2 v[94:95], v[20:21], off
	v_lshl_add_u64 v[16:17], s[4:5], 0, v[16:17]
	v_lshl_add_u64 v[20:21], s[6:7], 0, v[20:21]
	s_waitcnt vmcnt(54)
	v_mul_f32_e32 v96, v56, v12
	v_mul_f32_e32 v97, v57, v13
	s_waitcnt vmcnt(53)
	v_lshlrev_b32_e32 v22, 16, v29
	v_and_b32_e32 v23, 0xffff0000, v29
	v_fma_f32 v12, v56, v12, v22
	v_fma_f32 v13, v57, v13, v23
	v_cvt_pk_bf16_f32 v98, v96, v97
	global_store_dword v[18:19], v98, off
	v_lshl_add_u64 v[18:19], s[4:5], 0, v[18:19]
	s_waitcnt vmcnt(53)
	v_mul_f32_e32 v96, v58, v12
	v_mul_f32_e32 v97, v59, v13
	s_waitcnt vmcnt(52)
	v_lshlrev_b32_e32 v22, 16, v30
	v_and_b32_e32 v23, 0xffff0000, v30
	v_fma_f32 v12, v58, v12, v22
	v_fma_f32 v13, v59, v13, v23
	v_cvt_pk_bf16_f32 v98, v96, v97
	global_store_dword v[18:19], v98, off
	v_lshl_add_u64 v[18:19], s[4:5], 0, v[18:19]
	s_waitcnt vmcnt(52)
	v_mul_f32_e32 v96, v60, v12
	v_mul_f32_e32 v97, v61, v13
	s_waitcnt vmcnt(51)
	v_lshlrev_b32_e32 v22, 16, v31
	v_and_b32_e32 v23, 0xffff0000, v31
	v_fma_f32 v12, v60, v12, v22
	v_fma_f32 v13, v61, v13, v23
	v_cvt_pk_bf16_f32 v98, v96, v97
	global_store_dword v[18:19], v98, off
	v_lshl_add_u64 v[18:19], s[4:5], 0, v[18:19]
	s_waitcnt vmcnt(51)
	v_mul_f32_e32 v12, v62, v12
	v_mul_f32_e32 v13, v63, v13
	v_cvt_pk_bf16_f32 v98, v12, v13
	global_store_dword v[18:19], v98, off
	v_lshl_add_u64 v[18:19], s[4:5], 0, v[18:19]
	s_waitcnt vmcnt(43)
	v_lshlrev_b32_e32 v22, 16, v32
	v_and_b32_e32 v23, 0xffff0000, v32
	v_add_f32_e32 v12, v12, v22
	v_add_f32_e32 v13, v13, v23
	s_waitcnt vmcnt(42)
	v_mul_f32_e32 v96, v64, v12
	v_mul_f32_e32 v97, v65, v13
	s_waitcnt vmcnt(41)
	v_lshlrev_b32_e32 v22, 16, v33
	v_and_b32_e32 v23, 0xffff0000, v33
	v_fma_f32 v12, v64, v12, v22
	v_fma_f32 v13, v65, v13, v23
	v_cvt_pk_bf16_f32 v98, v96, v97
	global_store_dword v[18:19], v98, off
	v_lshl_add_u64 v[18:19], s[4:5], 0, v[18:19]
	s_waitcnt vmcnt(41)
	v_mul_f32_e32 v96, v66, v12
	v_mul_f32_e32 v97, v67, v13
	s_waitcnt vmcnt(40)
	v_lshlrev_b32_e32 v22, 16, v34
	v_and_b32_e32 v23, 0xffff0000, v34
	v_fma_f32 v12, v66, v12, v22
	v_fma_f32 v13, v67, v13, v23
	v_cvt_pk_bf16_f32 v98, v96, v97
	global_store_dword v[18:19], v98, off
	v_lshl_add_u64 v[18:19], s[4:5], 0, v[18:19]
	s_waitcnt vmcnt(40)
	v_mul_f32_e32 v96, v68, v12
	v_mul_f32_e32 v97, v69, v13
	s_waitcnt vmcnt(39)
	v_lshlrev_b32_e32 v22, 16, v35
	v_and_b32_e32 v23, 0xffff0000, v35
	v_fma_f32 v12, v68, v12, v22
	v_fma_f32 v13, v69, v13, v23
	v_cvt_pk_bf16_f32 v98, v96, v97
	global_store_dword v[18:19], v98, off
	v_lshl_add_u64 v[18:19], s[4:5], 0, v[18:19]
	s_waitcnt vmcnt(39)
	v_mul_f32_e32 v96, v70, v12
	v_mul_f32_e32 v97, v71, v13
	s_waitcnt vmcnt(38)
	v_lshlrev_b32_e32 v22, 16, v36
	v_and_b32_e32 v23, 0xffff0000, v36
	v_fma_f32 v12, v70, v12, v22
	v_fma_f32 v13, v71, v13, v23
	v_cvt_pk_bf16_f32 v98, v96, v97
	global_store_dword v[18:19], v98, off
	v_lshl_add_u64 v[18:19], s[4:5], 0, v[18:19]
	global_load_dword v24, v[16:17], off
	global_load_dwordx2 v[48:49], v[20:21], off
	v_lshl_add_u64 v[16:17], s[4:5], 0, v[16:17]
	v_lshl_add_u64 v[20:21], s[6:7], 0, v[20:21]
	global_load_dword v25, v[16:17], off
	global_load_dwordx2 v[50:51], v[20:21], off
	v_lshl_add_u64 v[16:17], s[4:5], 0, v[16:17]
	v_lshl_add_u64 v[20:21], s[6:7], 0, v[20:21]
	global_load_dword v26, v[16:17], off
	global_load_dwordx2 v[52:53], v[20:21], off
	v_lshl_add_u64 v[16:17], s[4:5], 0, v[16:17]
	v_lshl_add_u64 v[20:21], s[6:7], 0, v[20:21]
	global_load_dword v27, v[16:17], off
	global_load_dwordx2 v[54:55], v[20:21], off
	v_lshl_add_u64 v[16:17], s[4:5], 0, v[16:17]
	v_lshl_add_u64 v[20:21], s[6:7], 0, v[20:21]
	global_load_dword v28, v[16:17], off
	global_load_dwordx2 v[56:57], v[20:21], off
	v_lshl_add_u64 v[16:17], s[4:5], 0, v[16:17]
	v_lshl_add_u64 v[20:21], s[6:7], 0, v[20:21]
	global_load_dword v29, v[16:17], off
	global_load_dwordx2 v[58:59], v[20:21], off
	v_lshl_add_u64 v[16:17], s[4:5], 0, v[16:17]
	v_lshl_add_u64 v[20:21], s[6:7], 0, v[20:21]
	global_load_dword v30, v[16:17], off
	global_load_dwordx2 v[60:61], v[20:21], off
	v_lshl_add_u64 v[16:17], s[4:5], 0, v[16:17]
	v_lshl_add_u64 v[20:21], s[6:7], 0, v[20:21]
	global_load_dword v31, v[16:17], off
	global_load_dwordx2 v[62:63], v[20:21], off
	v_lshl_add_u64 v[16:17], s[4:5], 0, v[16:17]
	v_lshl_add_u64 v[20:21], s[6:7], 0, v[20:21]
	s_waitcnt vmcnt(54)
	v_mul_f32_e32 v96, v72, v12
	v_mul_f32_e32 v97, v73, v13
	s_waitcnt vmcnt(53)
	v_lshlrev_b32_e32 v22, 16, v37
	v_and_b32_e32 v23, 0xffff0000, v37
	v_fma_f32 v12, v72, v12, v22
	v_fma_f32 v13, v73, v13, v23
	v_cvt_pk_bf16_f32 v98, v96, v97
	global_store_dword v[18:19], v98, off
	v_lshl_add_u64 v[18:19], s[4:5], 0, v[18:19]
	s_waitcnt vmcnt(53)
	v_mul_f32_e32 v96, v74, v12
	v_mul_f32_e32 v97, v75, v13
	s_waitcnt vmcnt(52)
	v_lshlrev_b32_e32 v22, 16, v38
	v_and_b32_e32 v23, 0xffff0000, v38
	v_fma_f32 v12, v74, v12, v22
	v_fma_f32 v13, v75, v13, v23
	v_cvt_pk_bf16_f32 v98, v96, v97
	global_store_dword v[18:19], v98, off
	v_lshl_add_u64 v[18:19], s[4:5], 0, v[18:19]
	s_waitcnt vmcnt(52)
	v_mul_f32_e32 v96, v76, v12
	v_mul_f32_e32 v97, v77, v13
	s_waitcnt vmcnt(51)
	v_lshlrev_b32_e32 v22, 16, v39
	v_and_b32_e32 v23, 0xffff0000, v39
	v_fma_f32 v12, v76, v12, v22
	v_fma_f32 v13, v77, v13, v23
	v_cvt_pk_bf16_f32 v98, v96, v97
	global_store_dword v[18:19], v98, off
	v_lshl_add_u64 v[18:19], s[4:5], 0, v[18:19]
	s_waitcnt vmcnt(51)
	v_mul_f32_e32 v12, v78, v12
	v_mul_f32_e32 v13, v79, v13
	v_cvt_pk_bf16_f32 v98, v12, v13
	global_store_dword v[18:19], v98, off
	v_lshl_add_u64 v[18:19], s[4:5], 0, v[18:19]
	s_waitcnt vmcnt(43)
	v_lshlrev_b32_e32 v22, 16, v40
	v_and_b32_e32 v23, 0xffff0000, v40
	v_add_f32_e32 v12, v12, v22
	v_add_f32_e32 v13, v13, v23
	s_waitcnt vmcnt(42)
	v_mul_f32_e32 v96, v80, v12
	v_mul_f32_e32 v97, v81, v13
	s_waitcnt vmcnt(41)
	v_lshlrev_b32_e32 v22, 16, v41
	v_and_b32_e32 v23, 0xffff0000, v41
	v_fma_f32 v12, v80, v12, v22
	v_fma_f32 v13, v81, v13, v23
	v_cvt_pk_bf16_f32 v98, v96, v97
	global_store_dword v[18:19], v98, off
	v_lshl_add_u64 v[18:19], s[4:5], 0, v[18:19]
	s_waitcnt vmcnt(41)
	v_mul_f32_e32 v96, v82, v12
	v_mul_f32_e32 v97, v83, v13
	s_waitcnt vmcnt(40)
	v_lshlrev_b32_e32 v22, 16, v42
	v_and_b32_e32 v23, 0xffff0000, v42
	v_fma_f32 v12, v82, v12, v22
	v_fma_f32 v13, v83, v13, v23
	v_cvt_pk_bf16_f32 v98, v96, v97
	global_store_dword v[18:19], v98, off
	v_lshl_add_u64 v[18:19], s[4:5], 0, v[18:19]
	s_waitcnt vmcnt(40)
	v_mul_f32_e32 v96, v84, v12
	v_mul_f32_e32 v97, v85, v13
	s_waitcnt vmcnt(39)
	v_lshlrev_b32_e32 v22, 16, v43
	v_and_b32_e32 v23, 0xffff0000, v43
	v_fma_f32 v12, v84, v12, v22
	v_fma_f32 v13, v85, v13, v23
	v_cvt_pk_bf16_f32 v98, v96, v97
	global_store_dword v[18:19], v98, off
	v_lshl_add_u64 v[18:19], s[4:5], 0, v[18:19]
	s_waitcnt vmcnt(39)
	v_mul_f32_e32 v96, v86, v12
	v_mul_f32_e32 v97, v87, v13
	s_waitcnt vmcnt(38)
	v_lshlrev_b32_e32 v22, 16, v44
	v_and_b32_e32 v23, 0xffff0000, v44
	v_fma_f32 v12, v86, v12, v22
	v_fma_f32 v13, v87, v13, v23
	v_cvt_pk_bf16_f32 v98, v96, v97
	global_store_dword v[18:19], v98, off
	v_lshl_add_u64 v[18:19], s[4:5], 0, v[18:19]
	global_load_dword v32, v[16:17], off
	global_load_dwordx2 v[64:65], v[20:21], off
	v_lshl_add_u64 v[16:17], s[4:5], 0, v[16:17]
	v_lshl_add_u64 v[20:21], s[6:7], 0, v[20:21]
	global_load_dword v33, v[16:17], off
	global_load_dwordx2 v[66:67], v[20:21], off
	v_lshl_add_u64 v[16:17], s[4:5], 0, v[16:17]
	v_lshl_add_u64 v[20:21], s[6:7], 0, v[20:21]
	global_load_dword v34, v[16:17], off
	global_load_dwordx2 v[68:69], v[20:21], off
	v_lshl_add_u64 v[16:17], s[4:5], 0, v[16:17]
	v_lshl_add_u64 v[20:21], s[6:7], 0, v[20:21]
	global_load_dword v35, v[16:17], off
	global_load_dwordx2 v[70:71], v[20:21], off
	v_lshl_add_u64 v[16:17], s[4:5], 0, v[16:17]
	v_lshl_add_u64 v[20:21], s[6:7], 0, v[20:21]
	global_load_dword v36, v[16:17], off
	global_load_dwordx2 v[72:73], v[20:21], off
	v_lshl_add_u64 v[16:17], s[4:5], 0, v[16:17]
	v_lshl_add_u64 v[20:21], s[6:7], 0, v[20:21]
	global_load_dword v37, v[16:17], off
	global_load_dwordx2 v[74:75], v[20:21], off
	v_lshl_add_u64 v[16:17], s[4:5], 0, v[16:17]
	v_lshl_add_u64 v[20:21], s[6:7], 0, v[20:21]
	global_load_dword v38, v[16:17], off
	global_load_dwordx2 v[76:77], v[20:21], off
	v_lshl_add_u64 v[16:17], s[4:5], 0, v[16:17]
	v_lshl_add_u64 v[20:21], s[6:7], 0, v[20:21]
	global_load_dword v39, v[16:17], off
	global_load_dwordx2 v[78:79], v[20:21], off
	v_lshl_add_u64 v[16:17], s[4:5], 0, v[16:17]
	v_lshl_add_u64 v[20:21], s[6:7], 0, v[20:21]
	s_waitcnt vmcnt(54)
	v_mul_f32_e32 v96, v88, v12
	v_mul_f32_e32 v97, v89, v13
	s_waitcnt vmcnt(53)
	v_lshlrev_b32_e32 v22, 16, v45
	v_and_b32_e32 v23, 0xffff0000, v45
	v_fma_f32 v12, v88, v12, v22
	v_fma_f32 v13, v89, v13, v23
	v_cvt_pk_bf16_f32 v98, v96, v97
	global_store_dword v[18:19], v98, off
	v_lshl_add_u64 v[18:19], s[4:5], 0, v[18:19]
	s_waitcnt vmcnt(53)
	v_mul_f32_e32 v96, v90, v12
	v_mul_f32_e32 v97, v91, v13
	s_waitcnt vmcnt(52)
	v_lshlrev_b32_e32 v22, 16, v46
	v_and_b32_e32 v23, 0xffff0000, v46
	v_fma_f32 v12, v90, v12, v22
	v_fma_f32 v13, v91, v13, v23
	v_cvt_pk_bf16_f32 v98, v96, v97
	global_store_dword v[18:19], v98, off
	v_lshl_add_u64 v[18:19], s[4:5], 0, v[18:19]
	s_waitcnt vmcnt(52)
	v_mul_f32_e32 v96, v92, v12
	v_mul_f32_e32 v97, v93, v13
	s_waitcnt vmcnt(51)
	v_lshlrev_b32_e32 v22, 16, v47
	v_and_b32_e32 v23, 0xffff0000, v47
	v_fma_f32 v12, v92, v12, v22
	v_fma_f32 v13, v93, v13, v23
	v_cvt_pk_bf16_f32 v98, v96, v97
	global_store_dword v[18:19], v98, off
	v_lshl_add_u64 v[18:19], s[4:5], 0, v[18:19]
	s_waitcnt vmcnt(51)
	v_mul_f32_e32 v12, v94, v12
	v_mul_f32_e32 v13, v95, v13
	v_cvt_pk_bf16_f32 v98, v12, v13
	global_store_dword v[18:19], v98, off
	v_lshl_add_u64 v[18:19], s[4:5], 0, v[18:19]
	s_waitcnt vmcnt(43)
	v_lshlrev_b32_e32 v22, 16, v24
	v_and_b32_e32 v23, 0xffff0000, v24
	v_add_f32_e32 v12, v12, v22
	v_add_f32_e32 v13, v13, v23
	s_waitcnt vmcnt(42)
	v_mul_f32_e32 v96, v48, v12
	v_mul_f32_e32 v97, v49, v13
	s_waitcnt vmcnt(41)
	v_lshlrev_b32_e32 v22, 16, v25
	v_and_b32_e32 v23, 0xffff0000, v25
	v_fma_f32 v12, v48, v12, v22
	v_fma_f32 v13, v49, v13, v23
	v_cvt_pk_bf16_f32 v98, v96, v97
	global_store_dword v[18:19], v98, off
	v_lshl_add_u64 v[18:19], s[4:5], 0, v[18:19]
	s_waitcnt vmcnt(41)
	v_mul_f32_e32 v96, v50, v12
	v_mul_f32_e32 v97, v51, v13
	s_waitcnt vmcnt(40)
	v_lshlrev_b32_e32 v22, 16, v26
	v_and_b32_e32 v23, 0xffff0000, v26
	v_fma_f32 v12, v50, v12, v22
	v_fma_f32 v13, v51, v13, v23
	v_cvt_pk_bf16_f32 v98, v96, v97
	global_store_dword v[18:19], v98, off
	v_lshl_add_u64 v[18:19], s[4:5], 0, v[18:19]
	s_waitcnt vmcnt(40)
	v_mul_f32_e32 v96, v52, v12
	v_mul_f32_e32 v97, v53, v13
	s_waitcnt vmcnt(39)
	v_lshlrev_b32_e32 v22, 16, v27
	v_and_b32_e32 v23, 0xffff0000, v27
	v_fma_f32 v12, v52, v12, v22
	v_fma_f32 v13, v53, v13, v23
	v_cvt_pk_bf16_f32 v98, v96, v97
	global_store_dword v[18:19], v98, off
	v_lshl_add_u64 v[18:19], s[4:5], 0, v[18:19]
	s_waitcnt vmcnt(39)
	v_mul_f32_e32 v96, v54, v12
	v_mul_f32_e32 v97, v55, v13
	s_waitcnt vmcnt(38)
	v_lshlrev_b32_e32 v22, 16, v28
	v_and_b32_e32 v23, 0xffff0000, v28
	v_fma_f32 v12, v54, v12, v22
	v_fma_f32 v13, v55, v13, v23
	v_cvt_pk_bf16_f32 v98, v96, v97
	global_store_dword v[18:19], v98, off
	v_lshl_add_u64 v[18:19], s[4:5], 0, v[18:19]
	s_waitcnt vmcnt(38)
	v_mul_f32_e32 v96, v56, v12
	v_mul_f32_e32 v97, v57, v13
	s_waitcnt vmcnt(37)
	v_lshlrev_b32_e32 v22, 16, v29
	v_and_b32_e32 v23, 0xffff0000, v29
	v_fma_f32 v12, v56, v12, v22
	v_fma_f32 v13, v57, v13, v23
	v_cvt_pk_bf16_f32 v98, v96, v97
	global_store_dword v[18:19], v98, off
	v_lshl_add_u64 v[18:19], s[4:5], 0, v[18:19]
	s_waitcnt vmcnt(37)
	v_mul_f32_e32 v96, v58, v12
	v_mul_f32_e32 v97, v59, v13
	s_waitcnt vmcnt(36)
	v_lshlrev_b32_e32 v22, 16, v30
	v_and_b32_e32 v23, 0xffff0000, v30
	v_fma_f32 v12, v58, v12, v22
	v_fma_f32 v13, v59, v13, v23
	v_cvt_pk_bf16_f32 v98, v96, v97
	global_store_dword v[18:19], v98, off
	v_lshl_add_u64 v[18:19], s[4:5], 0, v[18:19]
	s_waitcnt vmcnt(36)
	v_mul_f32_e32 v96, v60, v12
	v_mul_f32_e32 v97, v61, v13
	s_waitcnt vmcnt(35)
	v_lshlrev_b32_e32 v22, 16, v31
	v_and_b32_e32 v23, 0xffff0000, v31
	v_fma_f32 v12, v60, v12, v22
	v_fma_f32 v13, v61, v13, v23
	v_cvt_pk_bf16_f32 v98, v96, v97
	global_store_dword v[18:19], v98, off
	v_lshl_add_u64 v[18:19], s[4:5], 0, v[18:19]
	s_waitcnt vmcnt(35)
	v_mul_f32_e32 v12, v62, v12
	v_mul_f32_e32 v13, v63, v13
	v_cvt_pk_bf16_f32 v98, v12, v13
	global_store_dword v[18:19], v98, off
	v_lshl_add_u64 v[18:19], s[4:5], 0, v[18:19]
	s_waitcnt vmcnt(27)
	v_lshlrev_b32_e32 v22, 16, v32
	v_and_b32_e32 v23, 0xffff0000, v32
	v_add_f32_e32 v12, v12, v22
	v_add_f32_e32 v13, v13, v23
	s_waitcnt vmcnt(26)
	v_mul_f32_e32 v96, v64, v12
	v_mul_f32_e32 v97, v65, v13
	s_waitcnt vmcnt(25)
	v_lshlrev_b32_e32 v22, 16, v33
	v_and_b32_e32 v23, 0xffff0000, v33
	v_fma_f32 v12, v64, v12, v22
	v_fma_f32 v13, v65, v13, v23
	v_cvt_pk_bf16_f32 v98, v96, v97
	global_store_dword v[18:19], v98, off
	v_lshl_add_u64 v[18:19], s[4:5], 0, v[18:19]
	s_waitcnt vmcnt(25)
	v_mul_f32_e32 v96, v66, v12
	v_mul_f32_e32 v97, v67, v13
	s_waitcnt vmcnt(24)
	v_lshlrev_b32_e32 v22, 16, v34
	v_and_b32_e32 v23, 0xffff0000, v34
	v_fma_f32 v12, v66, v12, v22
	v_fma_f32 v13, v67, v13, v23
	v_cvt_pk_bf16_f32 v98, v96, v97
	global_store_dword v[18:19], v98, off
	v_lshl_add_u64 v[18:19], s[4:5], 0, v[18:19]
	s_waitcnt vmcnt(24)
	v_mul_f32_e32 v96, v68, v12
	v_mul_f32_e32 v97, v69, v13
	s_waitcnt vmcnt(23)
	v_lshlrev_b32_e32 v22, 16, v35
	v_and_b32_e32 v23, 0xffff0000, v35
	v_fma_f32 v12, v68, v12, v22
	v_fma_f32 v13, v69, v13, v23
	v_cvt_pk_bf16_f32 v98, v96, v97
	global_store_dword v[18:19], v98, off
	v_lshl_add_u64 v[18:19], s[4:5], 0, v[18:19]
	s_waitcnt vmcnt(23)
	v_mul_f32_e32 v96, v70, v12
	v_mul_f32_e32 v97, v71, v13
	s_waitcnt vmcnt(22)
	v_lshlrev_b32_e32 v22, 16, v36
	v_and_b32_e32 v23, 0xffff0000, v36
	v_fma_f32 v12, v70, v12, v22
	v_fma_f32 v13, v71, v13, v23
	v_cvt_pk_bf16_f32 v98, v96, v97
	global_store_dword v[18:19], v98, off
	v_lshl_add_u64 v[18:19], s[4:5], 0, v[18:19]
	s_waitcnt vmcnt(22)
	v_mul_f32_e32 v96, v72, v12
	v_mul_f32_e32 v97, v73, v13
	s_waitcnt vmcnt(21)
	v_lshlrev_b32_e32 v22, 16, v37
	v_and_b32_e32 v23, 0xffff0000, v37
	v_fma_f32 v12, v72, v12, v22
	v_fma_f32 v13, v73, v13, v23
	v_cvt_pk_bf16_f32 v98, v96, v97
	global_store_dword v[18:19], v98, off
	v_lshl_add_u64 v[18:19], s[4:5], 0, v[18:19]
	s_waitcnt vmcnt(21)
	v_mul_f32_e32 v96, v74, v12
	v_mul_f32_e32 v97, v75, v13
	s_waitcnt vmcnt(20)
	v_lshlrev_b32_e32 v22, 16, v38
	v_and_b32_e32 v23, 0xffff0000, v38
	v_fma_f32 v12, v74, v12, v22
	v_fma_f32 v13, v75, v13, v23
	v_cvt_pk_bf16_f32 v98, v96, v97
	global_store_dword v[18:19], v98, off
	v_lshl_add_u64 v[18:19], s[4:5], 0, v[18:19]
	s_waitcnt vmcnt(20)
	v_mul_f32_e32 v96, v76, v12
	v_mul_f32_e32 v97, v77, v13
	s_waitcnt vmcnt(19)
	v_lshlrev_b32_e32 v22, 16, v39
	v_and_b32_e32 v23, 0xffff0000, v39
	v_fma_f32 v12, v76, v12, v22
	v_fma_f32 v13, v77, v13, v23
	v_cvt_pk_bf16_f32 v98, v96, v97
	global_store_dword v[18:19], v98, off
	v_lshl_add_u64 v[18:19], s[4:5], 0, v[18:19]
	s_waitcnt vmcnt(19)
	v_mul_f32_e32 v12, v78, v12
	v_mul_f32_e32 v13, v79, v13
	v_add_u32_e32 v2, s36, v2
	v_cmp_lt_i32_e32 vcc, s51, v2
	v_lshl_add_u64 v[4:5], v[4:5], 0, s[38:39]
	s_or_b64 s[44:45], vcc, s[44:45]
	v_add_u32_e32 v3, s37, v3
	s_andn2_b64 exec, exec, s[44:45]
	s_cbranch_execnz .LBB0_350
